# GEMM K-loops (FFN up, in-proj): per-segment s_setprio flips replaced by one static s_setprio 1 for waves 4..7 before the loop
# baseline (speedup 1.0000x reference)
.LBB0_81:
	s_ashr_i32 s61, s60, 31
	s_lshl_b64 s[24:25], s[60:61], 19
	v_readlane_b32 s30, v252, 3
	v_readlane_b32 s31, v252, 4
	s_add_u32 s64, s30, s24
	s_addc_u32 s65, s31, s25
	s_and_b64 s[24:25], s[62:63], exec
	s_cselect_b32 s0, s65, s35
	s_cselect_b32 s27, s64, s34
	s_ashr_i32 s59, s58, 31
	s_lshl_b64 s[24:25], s[58:59], 19
	s_add_u32 s24, s72, s24
	s_addc_u32 s25, s73, s25
	s_and_b64 s[30:31], s[62:63], exec
	s_cselect_b32 s30, s25, s67
	s_cselect_b32 s31, s24, s66
	s_add_u32 s34, s34, 0x40080
	s_addc_u32 s35, s35, 0
	s_add_u32 s59, s66, 0x100
	v_mov_b32_e32 v0, 0
	s_addc_u32 s61, s67, 0
	s_mov_b32 vcc_lo, -2
	v_mov_b32_e32 v1, v0
	v_mov_b32_e32 v2, v0
	v_mov_b32_e32 v3, v0
	v_mov_b32_e32 v8, v0
	v_mov_b32_e32 v9, v0
	v_mov_b32_e32 v10, v0
	v_mov_b32_e32 v11, v0
	v_mov_b32_e32 v16, v0
	v_mov_b32_e32 v17, v0
	v_mov_b32_e32 v18, v0
	v_mov_b32_e32 v19, v0
	v_mov_b32_e32 v24, v0
	v_mov_b32_e32 v25, v0
	v_mov_b32_e32 v26, v0
	v_mov_b32_e32 v27, v0
	v_mov_b32_e32 v38, v0
	v_mov_b32_e32 v39, v0
	v_mov_b32_e32 v40, v0
	v_mov_b32_e32 v41, v0
	v_mov_b32_e32 v46, v0
	v_mov_b32_e32 v47, v0
	v_mov_b32_e32 v48, v0
	v_mov_b32_e32 v49, v0
	v_mov_b32_e32 v54, v0
	v_mov_b32_e32 v55, v0
	v_mov_b32_e32 v56, v0
	v_mov_b32_e32 v57, v0
	v_mov_b32_e32 v62, v0
	v_mov_b32_e32 v63, v0
	v_mov_b32_e32 v64, v0
	v_mov_b32_e32 v65, v0
	v_mov_b32_e32 v4, v0
	v_mov_b32_e32 v5, v0
	v_mov_b32_e32 v6, v0
	v_mov_b32_e32 v7, v0
	v_mov_b32_e32 v12, v0
	v_mov_b32_e32 v13, v0
	v_mov_b32_e32 v14, v0
	v_mov_b32_e32 v15, v0
	v_mov_b32_e32 v20, v0
	v_mov_b32_e32 v21, v0
	v_mov_b32_e32 v22, v0
	v_mov_b32_e32 v23, v0
	v_mov_b32_e32 v28, v0
	v_mov_b32_e32 v29, v0
	v_mov_b32_e32 v30, v0
	v_mov_b32_e32 v31, v0
	v_mov_b32_e32 v42, v0
	v_mov_b32_e32 v43, v0
	v_mov_b32_e32 v44, v0
	v_mov_b32_e32 v45, v0
	v_mov_b32_e32 v50, v0
	v_mov_b32_e32 v51, v0
	v_mov_b32_e32 v52, v0
	v_mov_b32_e32 v53, v0
	v_mov_b32_e32 v58, v0
	v_mov_b32_e32 v59, v0
	v_mov_b32_e32 v60, v0
	v_mov_b32_e32 v61, v0
	v_mov_b32_e32 v66, v0
	v_mov_b32_e32 v67, v0
	v_mov_b32_e32 v68, v0
	v_mov_b32_e32 v69, v0
	v_mov_b32_e32 v70, v0
	v_mov_b32_e32 v71, v0
	v_mov_b32_e32 v72, v0
	v_mov_b32_e32 v73, v0
	v_mov_b32_e32 v78, v0
	v_mov_b32_e32 v79, v0
	v_mov_b32_e32 v80, v0
	v_mov_b32_e32 v81, v0
	v_mov_b32_e32 v86, v0
	v_mov_b32_e32 v87, v0
	v_mov_b32_e32 v88, v0
	v_mov_b32_e32 v89, v0
	v_mov_b32_e32 v94, v0
	v_mov_b32_e32 v95, v0
	v_mov_b32_e32 v96, v0
	v_mov_b32_e32 v97, v0
	v_mov_b32_e32 v102, v0
	v_mov_b32_e32 v103, v0
	v_mov_b32_e32 v104, v0
	v_mov_b32_e32 v105, v0
	v_mov_b32_e32 v110, v0
	v_mov_b32_e32 v111, v0
	v_mov_b32_e32 v112, v0
	v_mov_b32_e32 v113, v0
	v_mov_b32_e32 v118, v0
	v_mov_b32_e32 v119, v0
	v_mov_b32_e32 v120, v0
	v_mov_b32_e32 v121, v0
	v_mov_b32_e32 v126, v0
	v_mov_b32_e32 v127, v0
	v_mov_b32_e32 v128, v0
	v_mov_b32_e32 v129, v0
	v_mov_b32_e32 v74, v0
	v_mov_b32_e32 v75, v0
	v_mov_b32_e32 v76, v0
	v_mov_b32_e32 v77, v0
	v_mov_b32_e32 v82, v0
	v_mov_b32_e32 v83, v0
	v_mov_b32_e32 v84, v0
	v_mov_b32_e32 v85, v0
	v_mov_b32_e32 v90, v0
	v_mov_b32_e32 v91, v0
	v_mov_b32_e32 v92, v0
	v_mov_b32_e32 v93, v0
	v_mov_b32_e32 v98, v0
	v_mov_b32_e32 v99, v0
	v_mov_b32_e32 v100, v0
	v_mov_b32_e32 v101, v0
	v_mov_b32_e32 v106, v0
	v_mov_b32_e32 v107, v0
	v_mov_b32_e32 v108, v0
	v_mov_b32_e32 v109, v0
	v_mov_b32_e32 v114, v0
	v_mov_b32_e32 v115, v0
	v_mov_b32_e32 v116, v0
	v_mov_b32_e32 v117, v0
	v_mov_b32_e32 v122, v0
	v_mov_b32_e32 v123, v0
	v_mov_b32_e32 v124, v0
	v_mov_b32_e32 v125, v0
	v_mov_b32_e32 v130, v0
	v_mov_b32_e32 v131, v0
	v_mov_b32_e32 v132, v0
	v_mov_b32_e32 v133, v0
	v_readfirstlane_b32 s98, v226
	s_nop 3
	s_bitcmp1_b32 s98, 8
	s_cbranch_scc0 .Lmy_prio82
	s_setprio 1
.Lmy_prio82:
.LBB0_82:
	s_add_u32 s44, s34, 0xfffc0080
	s_addc_u32 s45, s35, -1
	s_add_i32 vcc_hi, 0, 0x10000
	s_cmp_eq_u32 vcc_lo, 12
	s_cselect_b32 s69, s0, s45
	s_cselect_b32 s68, s27, s44
	v_add_u32_e32 v149, vcc_hi, v146
	s_cselect_b32 s67, s30, s61
	s_cselect_b32 s66, s31, s59
	s_add_i32 s41, 0, 0x14000
	ds_read_b128 v[142:145], v149
	ds_read_b128 v[150:153], v149 offset:1024
	ds_read_b128 v[154:157], v149 offset:2048
	ds_read_b128 v[158:161], v149 offset:3072
	v_add_u32_e32 v149, s41, v146
	ds_read_b128 v[162:165], v149
	ds_read_b128 v[166:169], v149 offset:1024
	ds_read_b128 v[170:173], v149 offset:2048
	ds_read_b128 v[174:177], v149 offset:3072
	v_lshl_add_u64 v[216:217], s[34:35], 0, v[138:139]
	s_add_i32 m0, s51, 0xc000
	ds_read_b128 v[184:187], v148
	ds_read_b128 v[188:191], v148 offset:1024
	ds_read_b128 v[192:195], v148 offset:2048
	ds_read_b128 v[196:199], v148 offset:3072
	ds_read_b128 v[200:203], v148 offset:4096
	ds_read_b128 v[204:207], v148 offset:5120
	ds_read_b128 v[208:211], v148 offset:6144
	ds_read_b128 v[212:215], v148 offset:7168
	global_load_lds_dwordx4 v[216:217], off
	v_lshl_add_u64 v[216:217], s[34:35], 0, v[140:141]
	s_add_i32 m0, s51, 0xe000
	s_nop 0
	global_load_lds_dwordx4 v[216:217], off
	s_waitcnt vmcnt(8)
	s_waitcnt lgkmcnt(0)
	s_barrier
	s_waitcnt lgkmcnt(0)
	v_mfma_f32_16x16x32_bf16 v[130:133], v[142:145], v[184:187], v[130:133]
	v_mfma_f32_16x16x32_bf16 v[122:125], v[154:157], v[184:187], v[122:125]
	v_mfma_f32_16x16x32_bf16 v[114:117], v[142:145], v[192:195], v[114:117]
	v_mfma_f32_16x16x32_bf16 v[106:109], v[154:157], v[192:195], v[106:109]
	v_mfma_f32_16x16x32_bf16 v[98:101], v[142:145], v[200:203], v[98:101]
	v_mfma_f32_16x16x32_bf16 v[90:93], v[154:157], v[200:203], v[90:93]
	v_mfma_f32_16x16x32_bf16 v[82:85], v[142:145], v[208:211], v[82:85]
	v_mfma_f32_16x16x32_bf16 v[74:77], v[154:157], v[208:211], v[74:77]
	v_mfma_f32_16x16x32_bf16 v[130:133], v[150:153], v[188:191], v[130:133]
	v_mfma_f32_16x16x32_bf16 v[122:125], v[158:161], v[188:191], v[122:125]
	v_mfma_f32_16x16x32_bf16 v[114:117], v[150:153], v[196:199], v[114:117]
	v_mfma_f32_16x16x32_bf16 v[106:109], v[158:161], v[196:199], v[106:109]
	v_mfma_f32_16x16x32_bf16 v[98:101], v[150:153], v[204:207], v[98:101]
	v_mfma_f32_16x16x32_bf16 v[90:93], v[158:161], v[204:207], v[90:93]
	v_mfma_f32_16x16x32_bf16 v[82:85], v[150:153], v[212:215], v[82:85]
	v_mfma_f32_16x16x32_bf16 v[74:77], v[158:161], v[212:215], v[74:77]
	v_mfma_f32_16x16x32_bf16 v[126:129], v[162:165], v[184:187], v[126:129]
	v_mfma_f32_16x16x32_bf16 v[118:121], v[170:173], v[184:187], v[118:121]
	v_mfma_f32_16x16x32_bf16 v[110:113], v[162:165], v[192:195], v[110:113]
	v_mfma_f32_16x16x32_bf16 v[102:105], v[170:173], v[192:195], v[102:105]
	v_mfma_f32_16x16x32_bf16 v[94:97], v[162:165], v[200:203], v[94:97]
	v_mfma_f32_16x16x32_bf16 v[86:89], v[170:173], v[200:203], v[86:89]
	v_mfma_f32_16x16x32_bf16 v[78:81], v[162:165], v[208:211], v[78:81]
	v_mfma_f32_16x16x32_bf16 v[70:73], v[170:173], v[208:211], v[70:73]
	v_mfma_f32_16x16x32_bf16 v[126:129], v[166:169], v[188:191], v[126:129]
	v_mfma_f32_16x16x32_bf16 v[118:121], v[174:177], v[188:191], v[118:121]
	v_mfma_f32_16x16x32_bf16 v[110:113], v[166:169], v[196:199], v[110:113]
	v_mfma_f32_16x16x32_bf16 v[102:105], v[174:177], v[196:199], v[102:105]
	v_mfma_f32_16x16x32_bf16 v[94:97], v[166:169], v[204:207], v[94:97]
	v_mfma_f32_16x16x32_bf16 v[86:89], v[174:177], v[204:207], v[86:89]
	v_mfma_f32_16x16x32_bf16 v[78:81], v[166:169], v[212:215], v[78:81]
	v_mfma_f32_16x16x32_bf16 v[70:73], v[174:177], v[212:215], v[70:73]
	s_barrier
	s_add_i32 s44, vcc_hi, s74
	v_lshl_add_u64 v[216:217], s[66:67], 0, v[32:33]
	s_mov_b32 m0, s44
	ds_read_b128 v[184:187], v148 offset:16384
	ds_read_b128 v[188:191], v148 offset:17408
	ds_read_b128 v[192:195], v148 offset:18432
	ds_read_b128 v[196:199], v148 offset:19456
	ds_read_b128 v[200:203], v148 offset:20480
	ds_read_b128 v[204:207], v148 offset:21504
	ds_read_b128 v[208:211], v148 offset:22528
	ds_read_b128 v[212:215], v148 offset:23552
	global_load_lds_dwordx4 v[216:217], off
	s_add_i32 m0, s44, 0x2000
	s_add_u32 s44, s66, 0x40000
	v_lshl_add_u64 v[218:219], s[66:67], 0, v[136:137]
	s_addc_u32 s45, s67, 0
	s_add_i32 s41, s41, s74
	global_load_lds_dwordx4 v[218:219], off
	v_lshl_add_u64 v[220:221], s[44:45], 0, v[32:33]
	s_mov_b32 m0, s41
	v_lshl_add_u64 v[222:223], s[68:69], 0, v[134:135]
	global_load_lds_dwordx4 v[220:221], off
	v_lshl_add_u64 v[220:221], s[44:45], 0, v[136:137]
	s_add_i32 m0, s41, 0x2000
	s_nop 0
	global_load_lds_dwordx4 v[220:221], off
	v_lshl_add_u64 v[220:221], s[68:69], 0, v[34:35]
	s_mov_b32 m0, s51
	s_nop 0
	global_load_lds_dwordx4 v[220:221], off
	s_mov_b32 m0, s75
	s_nop 0
	global_load_lds_dwordx4 v[222:223], off
	s_waitcnt vmcnt(8)
	s_waitcnt lgkmcnt(0)
	s_barrier
	s_waitcnt lgkmcnt(0)
	v_mfma_f32_16x16x32_bf16 v[66:69], v[142:145], v[184:187], v[66:69]
	v_mfma_f32_16x16x32_bf16 v[58:61], v[154:157], v[184:187], v[58:61]
	v_mfma_f32_16x16x32_bf16 v[50:53], v[142:145], v[192:195], v[50:53]
	v_mfma_f32_16x16x32_bf16 v[42:45], v[154:157], v[192:195], v[42:45]
	v_mfma_f32_16x16x32_bf16 v[28:31], v[142:145], v[200:203], v[28:31]
	v_mfma_f32_16x16x32_bf16 v[20:23], v[154:157], v[200:203], v[20:23]
	v_mfma_f32_16x16x32_bf16 v[12:15], v[142:145], v[208:211], v[12:15]
	v_mfma_f32_16x16x32_bf16 v[4:7], v[154:157], v[208:211], v[4:7]
	v_mfma_f32_16x16x32_bf16 v[66:69], v[150:153], v[188:191], v[66:69]
	v_mfma_f32_16x16x32_bf16 v[58:61], v[158:161], v[188:191], v[58:61]
	v_mfma_f32_16x16x32_bf16 v[50:53], v[150:153], v[196:199], v[50:53]
	v_mfma_f32_16x16x32_bf16 v[42:45], v[158:161], v[196:199], v[42:45]
	v_mfma_f32_16x16x32_bf16 v[28:31], v[150:153], v[204:207], v[28:31]
	v_mfma_f32_16x16x32_bf16 v[20:23], v[158:161], v[204:207], v[20:23]
	v_mfma_f32_16x16x32_bf16 v[12:15], v[150:153], v[212:215], v[12:15]
	v_mfma_f32_16x16x32_bf16 v[4:7], v[158:161], v[212:215], v[4:7]
	v_mfma_f32_16x16x32_bf16 v[62:65], v[162:165], v[184:187], v[62:65]
	v_mfma_f32_16x16x32_bf16 v[54:57], v[170:173], v[184:187], v[54:57]
	v_mfma_f32_16x16x32_bf16 v[46:49], v[162:165], v[192:195], v[46:49]
	v_mfma_f32_16x16x32_bf16 v[38:41], v[170:173], v[192:195], v[38:41]
	v_mfma_f32_16x16x32_bf16 v[24:27], v[162:165], v[200:203], v[24:27]
	v_mfma_f32_16x16x32_bf16 v[16:19], v[170:173], v[200:203], v[16:19]
	v_mfma_f32_16x16x32_bf16 v[8:11], v[162:165], v[208:211], v[8:11]
	v_mfma_f32_16x16x32_bf16 v[0:3], v[170:173], v[208:211], v[0:3]
	v_mfma_f32_16x16x32_bf16 v[62:65], v[166:169], v[188:191], v[62:65]
	v_mfma_f32_16x16x32_bf16 v[54:57], v[174:177], v[188:191], v[54:57]
	v_mfma_f32_16x16x32_bf16 v[46:49], v[166:169], v[196:199], v[46:49]
	v_mfma_f32_16x16x32_bf16 v[38:41], v[174:177], v[196:199], v[38:41]
	v_mfma_f32_16x16x32_bf16 v[24:27], v[166:169], v[204:207], v[24:27]
	v_mfma_f32_16x16x32_bf16 v[16:19], v[174:177], v[204:207], v[16:19]
	v_mfma_f32_16x16x32_bf16 v[8:11], v[166:169], v[212:215], v[8:11]
	v_mfma_f32_16x16x32_bf16 v[0:3], v[174:177], v[212:215], v[0:3]
	s_barrier
	s_add_i32 s41, 0, 0x18000
	v_add_u32_e32 v149, s41, v146
	s_add_i32 vcc_hi, 0, 0x1c000
	ds_read_b128 v[142:145], v149
	ds_read_b128 v[150:153], v149 offset:1024
	ds_read_b128 v[154:157], v149 offset:2048
	ds_read_b128 v[158:161], v149 offset:3072
	v_add_u32_e32 v149, vcc_hi, v146
	ds_read_b128 v[162:165], v149
	ds_read_b128 v[166:169], v149 offset:1024
	ds_read_b128 v[170:173], v149 offset:2048
	ds_read_b128 v[174:177], v149 offset:3072
	s_add_u32 s44, s68, 0x40000
	s_addc_u32 s45, s69, 0
	s_mov_b32 m0, s76
	v_lshl_add_u64 v[224:225], s[44:45], 0, v[34:35]
	ds_read_b128 v[184:187], v148 offset:32768
	ds_read_b128 v[188:191], v148 offset:33792
	ds_read_b128 v[192:195], v148 offset:34816
	ds_read_b128 v[196:199], v148 offset:35840
	ds_read_b128 v[200:203], v148 offset:36864
	ds_read_b128 v[204:207], v148 offset:37888
	ds_read_b128 v[208:211], v148 offset:38912
	ds_read_b128 v[212:215], v148 offset:39936
	global_load_lds_dwordx4 v[224:225], off
	v_lshl_add_u64 v[224:225], s[44:45], 0, v[134:135]
	s_mov_b32 m0, s77
	s_nop 0
	global_load_lds_dwordx4 v[224:225], off
	s_waitcnt vmcnt(8)
	s_waitcnt lgkmcnt(0)
	s_barrier
	s_waitcnt lgkmcnt(0)
	v_mfma_f32_16x16x32_bf16 v[130:133], v[142:145], v[184:187], v[130:133]
	v_mfma_f32_16x16x32_bf16 v[122:125], v[154:157], v[184:187], v[122:125]
	v_mfma_f32_16x16x32_bf16 v[114:117], v[142:145], v[192:195], v[114:117]
	v_mfma_f32_16x16x32_bf16 v[106:109], v[154:157], v[192:195], v[106:109]
	v_mfma_f32_16x16x32_bf16 v[98:101], v[142:145], v[200:203], v[98:101]
	v_mfma_f32_16x16x32_bf16 v[90:93], v[154:157], v[200:203], v[90:93]
	v_mfma_f32_16x16x32_bf16 v[82:85], v[142:145], v[208:211], v[82:85]
	v_mfma_f32_16x16x32_bf16 v[74:77], v[154:157], v[208:211], v[74:77]
	v_mfma_f32_16x16x32_bf16 v[130:133], v[150:153], v[188:191], v[130:133]
	v_mfma_f32_16x16x32_bf16 v[122:125], v[158:161], v[188:191], v[122:125]
	v_mfma_f32_16x16x32_bf16 v[114:117], v[150:153], v[196:199], v[114:117]
	v_mfma_f32_16x16x32_bf16 v[106:109], v[158:161], v[196:199], v[106:109]
	v_mfma_f32_16x16x32_bf16 v[98:101], v[150:153], v[204:207], v[98:101]
	v_mfma_f32_16x16x32_bf16 v[90:93], v[158:161], v[204:207], v[90:93]
	v_mfma_f32_16x16x32_bf16 v[82:85], v[150:153], v[212:215], v[82:85]
	v_mfma_f32_16x16x32_bf16 v[74:77], v[158:161], v[212:215], v[74:77]
	v_mfma_f32_16x16x32_bf16 v[126:129], v[162:165], v[184:187], v[126:129]
	v_mfma_f32_16x16x32_bf16 v[118:121], v[170:173], v[184:187], v[118:121]
	v_mfma_f32_16x16x32_bf16 v[110:113], v[162:165], v[192:195], v[110:113]
	v_mfma_f32_16x16x32_bf16 v[102:105], v[170:173], v[192:195], v[102:105]
	v_mfma_f32_16x16x32_bf16 v[94:97], v[162:165], v[200:203], v[94:97]
	v_mfma_f32_16x16x32_bf16 v[86:89], v[170:173], v[200:203], v[86:89]
	v_mfma_f32_16x16x32_bf16 v[78:81], v[162:165], v[208:211], v[78:81]
	v_mfma_f32_16x16x32_bf16 v[70:73], v[170:173], v[208:211], v[70:73]
	v_mfma_f32_16x16x32_bf16 v[126:129], v[166:169], v[188:191], v[126:129]
	v_mfma_f32_16x16x32_bf16 v[118:121], v[174:177], v[188:191], v[118:121]
	v_mfma_f32_16x16x32_bf16 v[110:113], v[166:169], v[196:199], v[110:113]
	v_mfma_f32_16x16x32_bf16 v[102:105], v[174:177], v[196:199], v[102:105]
	v_mfma_f32_16x16x32_bf16 v[94:97], v[166:169], v[204:207], v[94:97]
	v_mfma_f32_16x16x32_bf16 v[86:89], v[174:177], v[204:207], v[86:89]
	v_mfma_f32_16x16x32_bf16 v[78:81], v[166:169], v[212:215], v[78:81]
	v_mfma_f32_16x16x32_bf16 v[70:73], v[174:177], v[212:215], v[70:73]
	s_barrier
	s_add_i32 s41, s41, s74
	v_lshl_add_u64 v[216:217], v[216:217], 0, s[88:89]
	s_mov_b32 m0, s41
	ds_read_b128 v[184:187], v148 offset:49152
	ds_read_b128 v[188:191], v148 offset:50176
	ds_read_b128 v[192:195], v148 offset:51200
	ds_read_b128 v[196:199], v148 offset:52224
	ds_read_b128 v[200:203], v148 offset:53248
	ds_read_b128 v[204:207], v148 offset:54272
	ds_read_b128 v[208:211], v148 offset:55296
	ds_read_b128 v[212:215], v148 offset:56320
	global_load_lds_dwordx4 v[216:217], off
	s_add_i32 m0, s41, 0x2000
	s_add_u32 s44, s66, 0x40080
	v_lshl_add_u64 v[216:217], v[218:219], 0, s[88:89]
	s_addc_u32 s45, s67, 0
	s_add_i32 s41, vcc_hi, s74
	global_load_lds_dwordx4 v[216:217], off
	v_lshl_add_u64 v[216:217], s[44:45], 0, v[32:33]
	s_mov_b32 m0, s41
	s_nop 0
	global_load_lds_dwordx4 v[216:217], off
	v_lshl_add_u64 v[216:217], s[44:45], 0, v[136:137]
	s_add_i32 m0, s41, 0x2000
	s_nop 0
	global_load_lds_dwordx4 v[216:217], off
	v_lshl_add_u64 v[216:217], v[220:221], 0, s[88:89]
	s_mov_b32 m0, s78
	s_nop 0
	global_load_lds_dwordx4 v[216:217], off
	v_lshl_add_u64 v[216:217], v[222:223], 0, s[88:89]
	s_mov_b32 m0, s79
	s_nop 0
	global_load_lds_dwordx4 v[216:217], off
	s_waitcnt vmcnt(8)
	s_waitcnt lgkmcnt(0)
	s_barrier
	s_waitcnt lgkmcnt(0)
	v_mfma_f32_16x16x32_bf16 v[66:69], v[142:145], v[184:187], v[66:69]
	v_mfma_f32_16x16x32_bf16 v[58:61], v[154:157], v[184:187], v[58:61]
	v_mfma_f32_16x16x32_bf16 v[50:53], v[142:145], v[192:195], v[50:53]
	v_mfma_f32_16x16x32_bf16 v[42:45], v[154:157], v[192:195], v[42:45]
	v_mfma_f32_16x16x32_bf16 v[28:31], v[142:145], v[200:203], v[28:31]
	v_mfma_f32_16x16x32_bf16 v[20:23], v[154:157], v[200:203], v[20:23]
	v_mfma_f32_16x16x32_bf16 v[12:15], v[142:145], v[208:211], v[12:15]
	v_mfma_f32_16x16x32_bf16 v[4:7], v[154:157], v[208:211], v[4:7]
	v_mfma_f32_16x16x32_bf16 v[66:69], v[150:153], v[188:191], v[66:69]
	v_mfma_f32_16x16x32_bf16 v[58:61], v[158:161], v[188:191], v[58:61]
	v_mfma_f32_16x16x32_bf16 v[50:53], v[150:153], v[196:199], v[50:53]
	v_mfma_f32_16x16x32_bf16 v[42:45], v[158:161], v[196:199], v[42:45]
	v_mfma_f32_16x16x32_bf16 v[28:31], v[150:153], v[204:207], v[28:31]
	v_mfma_f32_16x16x32_bf16 v[20:23], v[158:161], v[204:207], v[20:23]
	v_mfma_f32_16x16x32_bf16 v[12:15], v[150:153], v[212:215], v[12:15]
	v_mfma_f32_16x16x32_bf16 v[4:7], v[158:161], v[212:215], v[4:7]
	v_mfma_f32_16x16x32_bf16 v[62:65], v[162:165], v[184:187], v[62:65]
	v_mfma_f32_16x16x32_bf16 v[54:57], v[170:173], v[184:187], v[54:57]
	v_mfma_f32_16x16x32_bf16 v[46:49], v[162:165], v[192:195], v[46:49]
	v_mfma_f32_16x16x32_bf16 v[38:41], v[170:173], v[192:195], v[38:41]
	v_mfma_f32_16x16x32_bf16 v[24:27], v[162:165], v[200:203], v[24:27]
	v_mfma_f32_16x16x32_bf16 v[16:19], v[170:173], v[200:203], v[16:19]
	v_mfma_f32_16x16x32_bf16 v[8:11], v[162:165], v[208:211], v[8:11]
	v_mfma_f32_16x16x32_bf16 v[0:3], v[170:173], v[208:211], v[0:3]
	v_mfma_f32_16x16x32_bf16 v[62:65], v[166:169], v[188:191], v[62:65]
	v_mfma_f32_16x16x32_bf16 v[54:57], v[174:177], v[188:191], v[54:57]
	v_mfma_f32_16x16x32_bf16 v[46:49], v[166:169], v[196:199], v[46:49]
	v_mfma_f32_16x16x32_bf16 v[38:41], v[174:177], v[196:199], v[38:41]
	v_mfma_f32_16x16x32_bf16 v[24:27], v[166:169], v[204:207], v[24:27]
	v_mfma_f32_16x16x32_bf16 v[16:19], v[174:177], v[204:207], v[16:19]
	v_mfma_f32_16x16x32_bf16 v[8:11], v[166:169], v[212:215], v[8:11]
	v_mfma_f32_16x16x32_bf16 v[0:3], v[174:177], v[212:215], v[0:3]
	s_barrier
	s_add_i32 vcc_lo, vcc_lo, 2
	s_add_u32 s34, s34, 0x100
	s_addc_u32 s35, s35, 0
	s_add_u32 s59, s59, 0x100
	s_addc_u32 s61, s61, 0
	s_cmp_gt_u32 vcc_lo, 13
	s_cbranch_scc0 .LBB0_82
	s_setprio 0
	s_and_b64 vcc, exec, s[54:55]
	s_cbranch_vccz .LBB0_85
	s_barrier

.LBB0_183:
	s_ashr_i32 s57, s56, 31
	s_lshl_b64 s[30:31], s[56:57], 19
	v_readlane_b32 s50, v252, 3
	v_readlane_b32 s51, v252, 4
	s_add_u32 s58, s50, s30
	s_addc_u32 s59, s51, s31
	s_and_b64 s[30:31], s[46:47], exec
	s_cselect_b32 s0, s59, s27
	s_cselect_b32 s30, s58, s26
	s_ashr_i32 s55, s54, 31
	s_lshl_b64 s[60:61], s[54:55], 19
	s_add_u32 s60, s68, s60
	s_addc_u32 s61, s69, s61
	s_and_b64 s[66:67], s[46:47], exec
	s_cselect_b32 s31, s61, s35
	s_cselect_b32 s55, s60, s34
	s_add_u32 s26, s26, 0x40080
	s_addc_u32 s27, s27, 0
	s_add_u32 s57, s34, 0x100
	v_mov_b32_e32 v0, 0
	s_addc_u32 vcc_lo, s35, 0
	s_mov_b32 vcc_hi, -2
	v_mov_b32_e32 v1, v0
	v_mov_b32_e32 v2, v0
	v_mov_b32_e32 v3, v0
	v_mov_b32_e32 v4, v0
	v_mov_b32_e32 v5, v0
	v_mov_b32_e32 v6, v0
	v_mov_b32_e32 v7, v0
	v_mov_b32_e32 v8, v0
	v_mov_b32_e32 v9, v0
	v_mov_b32_e32 v10, v0
	v_mov_b32_e32 v11, v0
	v_mov_b32_e32 v16, v0
	v_mov_b32_e32 v17, v0
	v_mov_b32_e32 v18, v0
	v_mov_b32_e32 v19, v0
	v_mov_b32_e32 v24, v0
	v_mov_b32_e32 v25, v0
	v_mov_b32_e32 v26, v0
	v_mov_b32_e32 v27, v0
	v_mov_b32_e32 v38, v0
	v_mov_b32_e32 v39, v0
	v_mov_b32_e32 v40, v0
	v_mov_b32_e32 v41, v0
	v_mov_b32_e32 v46, v0
	v_mov_b32_e32 v47, v0
	v_mov_b32_e32 v48, v0
	v_mov_b32_e32 v49, v0
	v_mov_b32_e32 v54, v0
	v_mov_b32_e32 v55, v0
	v_mov_b32_e32 v56, v0
	v_mov_b32_e32 v57, v0
	v_mov_b32_e32 v12, v0
	v_mov_b32_e32 v13, v0
	v_mov_b32_e32 v14, v0
	v_mov_b32_e32 v15, v0
	v_mov_b32_e32 v20, v0
	v_mov_b32_e32 v21, v0
	v_mov_b32_e32 v22, v0
	v_mov_b32_e32 v23, v0
	v_mov_b32_e32 v28, v0
	v_mov_b32_e32 v29, v0
	v_mov_b32_e32 v30, v0
	v_mov_b32_e32 v31, v0
	v_mov_b32_e32 v42, v0
	v_mov_b32_e32 v43, v0
	v_mov_b32_e32 v44, v0
	v_mov_b32_e32 v45, v0
	v_mov_b32_e32 v50, v0
	v_mov_b32_e32 v51, v0
	v_mov_b32_e32 v52, v0
	v_mov_b32_e32 v53, v0
	v_mov_b32_e32 v58, v0
	v_mov_b32_e32 v59, v0
	v_mov_b32_e32 v60, v0
	v_mov_b32_e32 v61, v0
	v_mov_b32_e32 v62, v0
	v_mov_b32_e32 v63, v0
	v_mov_b32_e32 v64, v0
	v_mov_b32_e32 v65, v0
	v_mov_b32_e32 v66, v0
	v_mov_b32_e32 v67, v0
	v_mov_b32_e32 v68, v0
	v_mov_b32_e32 v69, v0
	v_mov_b32_e32 v70, v0
	v_mov_b32_e32 v71, v0
	v_mov_b32_e32 v72, v0
	v_mov_b32_e32 v73, v0
	v_mov_b32_e32 v74, v0
	v_mov_b32_e32 v75, v0
	v_mov_b32_e32 v76, v0
	v_mov_b32_e32 v77, v0
	v_mov_b32_e32 v82, v0
	v_mov_b32_e32 v83, v0
	v_mov_b32_e32 v84, v0
	v_mov_b32_e32 v85, v0
	v_mov_b32_e32 v90, v0
	v_mov_b32_e32 v91, v0
	v_mov_b32_e32 v92, v0
	v_mov_b32_e32 v93, v0
	v_mov_b32_e32 v94, v0
	v_mov_b32_e32 v95, v0
	v_mov_b32_e32 v96, v0
	v_mov_b32_e32 v97, v0
	v_mov_b32_e32 v102, v0
	v_mov_b32_e32 v103, v0
	v_mov_b32_e32 v104, v0
	v_mov_b32_e32 v105, v0
	v_mov_b32_e32 v110, v0
	v_mov_b32_e32 v111, v0
	v_mov_b32_e32 v112, v0
	v_mov_b32_e32 v113, v0
	v_mov_b32_e32 v118, v0
	v_mov_b32_e32 v119, v0
	v_mov_b32_e32 v120, v0
	v_mov_b32_e32 v121, v0
	v_mov_b32_e32 v78, v0
	v_mov_b32_e32 v79, v0
	v_mov_b32_e32 v80, v0
	v_mov_b32_e32 v81, v0
	v_mov_b32_e32 v86, v0
	v_mov_b32_e32 v87, v0
	v_mov_b32_e32 v88, v0
	v_mov_b32_e32 v89, v0
	v_mov_b32_e32 v98, v0
	v_mov_b32_e32 v99, v0
	v_mov_b32_e32 v100, v0
	v_mov_b32_e32 v101, v0
	v_mov_b32_e32 v106, v0
	v_mov_b32_e32 v107, v0
	v_mov_b32_e32 v108, v0
	v_mov_b32_e32 v109, v0
	v_mov_b32_e32 v114, v0
	v_mov_b32_e32 v115, v0
	v_mov_b32_e32 v116, v0
	v_mov_b32_e32 v117, v0
	v_mov_b32_e32 v122, v0
	v_mov_b32_e32 v123, v0
	v_mov_b32_e32 v124, v0
	v_mov_b32_e32 v125, v0
	v_mov_b32_e32 v126, v0
	v_mov_b32_e32 v127, v0
	v_mov_b32_e32 v128, v0
	v_mov_b32_e32 v129, v0
	v_mov_b32_e32 v130, v0
	v_mov_b32_e32 v131, v0
	v_mov_b32_e32 v132, v0
	v_mov_b32_e32 v133, v0
	v_readfirstlane_b32 s98, v226
	s_nop 3
	s_bitcmp1_b32 s98, 8
	s_cbranch_scc0 .Lmy_prio184
	s_setprio 1
.Lmy_prio184:
.LBB0_184:
	s_add_u32 s34, s26, 0xfffc0080
	s_addc_u32 s35, s27, -1
	s_add_i32 s50, 0, 0x10000
	s_cmp_eq_u32 vcc_hi, 12
	s_cselect_b32 s67, s0, s35
	s_cselect_b32 s66, s30, s34
	s_cselect_b32 s35, s31, vcc_lo
	s_cselect_b32 s34, s55, s57
	s_add_i32 s72, 0, 0x14000
	v_add_u32_e32 v160, s50, v148
	v_add_u32_e32 v176, s72, v148
	ds_read_b128 v[144:147], v160
	ds_read_b128 v[152:155], v160 offset:1024
	ds_read_b128 v[156:159], v160 offset:2048
	ds_read_b128 v[160:163], v160 offset:3072
	ds_read_b128 v[164:167], v176
	ds_read_b128 v[168:171], v176 offset:1024
	ds_read_b128 v[172:175], v176 offset:2048
	ds_read_b128 v[184:187], v176 offset:3072
	v_lshl_add_u64 v[176:177], s[26:27], 0, v[140:141]
	s_add_i32 m0, s63, 0xc000
	ds_read_b128 v[188:191], v150
	ds_read_b128 v[192:195], v150 offset:1024
	ds_read_b128 v[196:199], v150 offset:2048
	ds_read_b128 v[200:203], v150 offset:3072
	ds_read_b128 v[204:207], v150 offset:4096
	ds_read_b128 v[208:211], v150 offset:5120
	ds_read_b128 v[212:215], v150 offset:6144
	ds_read_b128 v[216:219], v150 offset:7168
	global_load_lds_dwordx4 v[176:177], off
	v_lshl_add_u64 v[176:177], s[26:27], 0, v[142:143]
	s_add_i32 m0, s63, 0xe000
	s_nop 0
	global_load_lds_dwordx4 v[176:177], off
	s_waitcnt vmcnt(8)
	s_waitcnt lgkmcnt(0)
	s_barrier
	s_waitcnt lgkmcnt(0)
	v_mfma_f32_16x16x32_bf16 v[130:133], v[144:147], v[188:191], v[130:133]
	v_mfma_f32_16x16x32_bf16 v[126:129], v[156:159], v[188:191], v[126:129]
	v_mfma_f32_16x16x32_bf16 v[122:125], v[144:147], v[196:199], v[122:125]
	v_mfma_f32_16x16x32_bf16 v[114:117], v[156:159], v[196:199], v[114:117]
	v_mfma_f32_16x16x32_bf16 v[106:109], v[144:147], v[204:207], v[106:109]
	v_mfma_f32_16x16x32_bf16 v[98:101], v[156:159], v[204:207], v[98:101]
	v_mfma_f32_16x16x32_bf16 v[86:89], v[144:147], v[212:215], v[86:89]
	v_mfma_f32_16x16x32_bf16 v[78:81], v[156:159], v[212:215], v[78:81]
	v_mfma_f32_16x16x32_bf16 v[130:133], v[152:155], v[192:195], v[130:133]
	v_mfma_f32_16x16x32_bf16 v[126:129], v[160:163], v[192:195], v[126:129]
	v_mfma_f32_16x16x32_bf16 v[122:125], v[152:155], v[200:203], v[122:125]
	v_mfma_f32_16x16x32_bf16 v[114:117], v[160:163], v[200:203], v[114:117]
	v_mfma_f32_16x16x32_bf16 v[106:109], v[152:155], v[208:211], v[106:109]
	v_mfma_f32_16x16x32_bf16 v[98:101], v[160:163], v[208:211], v[98:101]
	v_mfma_f32_16x16x32_bf16 v[86:89], v[152:155], v[216:219], v[86:89]
	v_mfma_f32_16x16x32_bf16 v[78:81], v[160:163], v[216:219], v[78:81]
	v_mfma_f32_16x16x32_bf16 v[118:121], v[164:167], v[188:191], v[118:121]
	v_mfma_f32_16x16x32_bf16 v[110:113], v[172:175], v[188:191], v[110:113]
	v_mfma_f32_16x16x32_bf16 v[102:105], v[164:167], v[196:199], v[102:105]
	v_mfma_f32_16x16x32_bf16 v[94:97], v[172:175], v[196:199], v[94:97]
	v_mfma_f32_16x16x32_bf16 v[90:93], v[164:167], v[204:207], v[90:93]
	v_mfma_f32_16x16x32_bf16 v[82:85], v[172:175], v[204:207], v[82:85]
	v_mfma_f32_16x16x32_bf16 v[74:77], v[164:167], v[212:215], v[74:77]
	v_mfma_f32_16x16x32_bf16 v[70:73], v[172:175], v[212:215], v[70:73]
	v_mfma_f32_16x16x32_bf16 v[118:121], v[168:171], v[192:195], v[118:121]
	v_mfma_f32_16x16x32_bf16 v[110:113], v[184:187], v[192:195], v[110:113]
	v_mfma_f32_16x16x32_bf16 v[102:105], v[168:171], v[200:203], v[102:105]
	v_mfma_f32_16x16x32_bf16 v[94:97], v[184:187], v[200:203], v[94:97]
	v_mfma_f32_16x16x32_bf16 v[90:93], v[168:171], v[208:211], v[90:93]
	v_mfma_f32_16x16x32_bf16 v[82:85], v[184:187], v[208:211], v[82:85]
	v_mfma_f32_16x16x32_bf16 v[74:77], v[168:171], v[216:219], v[74:77]
	v_mfma_f32_16x16x32_bf16 v[70:73], v[184:187], v[216:219], v[70:73]
	s_barrier
	s_add_i32 s50, s50, s70
	v_lshl_add_u64 v[176:177], s[34:35], 0, v[136:137]
	s_mov_b32 m0, s50
	ds_read_b128 v[188:191], v150 offset:16384
	ds_read_b128 v[192:195], v150 offset:17408
	ds_read_b128 v[196:199], v150 offset:18432
	ds_read_b128 v[200:203], v150 offset:19456
	ds_read_b128 v[204:207], v150 offset:20480
	ds_read_b128 v[208:211], v150 offset:21504
	ds_read_b128 v[212:215], v150 offset:22528
	ds_read_b128 v[216:219], v150 offset:23552
	global_load_lds_dwordx4 v[176:177], off
	s_add_i32 m0, s50, 0x2000
	s_add_u32 s50, s34, 0x40000
	v_lshl_add_u64 v[220:221], s[34:35], 0, v[34:35]
	s_addc_u32 s51, s35, 0
	s_add_i32 s72, s72, s70
	global_load_lds_dwordx4 v[220:221], off
	v_lshl_add_u64 v[222:223], s[50:51], 0, v[136:137]
	s_mov_b32 m0, s72
	v_lshl_add_u64 v[224:225], s[66:67], 0, v[134:135]
	global_load_lds_dwordx4 v[222:223], off
	v_lshl_add_u64 v[222:223], s[50:51], 0, v[34:35]
	s_add_i32 m0, s72, 0x2000
	s_nop 0
	global_load_lds_dwordx4 v[222:223], off
	v_lshl_add_u64 v[222:223], s[66:67], 0, v[138:139]
	s_mov_b32 m0, s63
	s_nop 0
	global_load_lds_dwordx4 v[222:223], off
	s_mov_b32 m0, s65
	s_nop 0
	global_load_lds_dwordx4 v[224:225], off
	s_waitcnt vmcnt(8)
	s_waitcnt lgkmcnt(0)
	s_barrier
	s_waitcnt lgkmcnt(0)
	v_mfma_f32_16x16x32_bf16 v[66:69], v[144:147], v[188:191], v[66:69]
	v_mfma_f32_16x16x32_bf16 v[62:65], v[156:159], v[188:191], v[62:65]
	v_mfma_f32_16x16x32_bf16 v[58:61], v[144:147], v[196:199], v[58:61]
	v_mfma_f32_16x16x32_bf16 v[50:53], v[156:159], v[196:199], v[50:53]
	v_mfma_f32_16x16x32_bf16 v[42:45], v[144:147], v[204:207], v[42:45]
	v_mfma_f32_16x16x32_bf16 v[28:31], v[156:159], v[204:207], v[28:31]
	v_mfma_f32_16x16x32_bf16 v[20:23], v[144:147], v[212:215], v[20:23]
	v_mfma_f32_16x16x32_bf16 v[12:15], v[156:159], v[212:215], v[12:15]
	v_mfma_f32_16x16x32_bf16 v[66:69], v[152:155], v[192:195], v[66:69]
	v_mfma_f32_16x16x32_bf16 v[62:65], v[160:163], v[192:195], v[62:65]
	v_mfma_f32_16x16x32_bf16 v[58:61], v[152:155], v[200:203], v[58:61]
	v_mfma_f32_16x16x32_bf16 v[50:53], v[160:163], v[200:203], v[50:53]
	v_mfma_f32_16x16x32_bf16 v[42:45], v[152:155], v[208:211], v[42:45]
	v_mfma_f32_16x16x32_bf16 v[28:31], v[160:163], v[208:211], v[28:31]
	v_mfma_f32_16x16x32_bf16 v[20:23], v[152:155], v[216:219], v[20:23]
	v_mfma_f32_16x16x32_bf16 v[12:15], v[160:163], v[216:219], v[12:15]
	v_mfma_f32_16x16x32_bf16 v[54:57], v[164:167], v[188:191], v[54:57]
	v_mfma_f32_16x16x32_bf16 v[46:49], v[172:175], v[188:191], v[46:49]
	v_mfma_f32_16x16x32_bf16 v[38:41], v[164:167], v[196:199], v[38:41]
	v_mfma_f32_16x16x32_bf16 v[24:27], v[172:175], v[196:199], v[24:27]
	v_mfma_f32_16x16x32_bf16 v[16:19], v[164:167], v[204:207], v[16:19]
	v_mfma_f32_16x16x32_bf16 v[8:11], v[172:175], v[204:207], v[8:11]
	v_mfma_f32_16x16x32_bf16 v[4:7], v[164:167], v[212:215], v[4:7]
	v_mfma_f32_16x16x32_bf16 v[0:3], v[172:175], v[212:215], v[0:3]
	v_mfma_f32_16x16x32_bf16 v[54:57], v[168:171], v[192:195], v[54:57]
	v_mfma_f32_16x16x32_bf16 v[46:49], v[184:187], v[192:195], v[46:49]
	v_mfma_f32_16x16x32_bf16 v[38:41], v[168:171], v[200:203], v[38:41]
	v_mfma_f32_16x16x32_bf16 v[24:27], v[184:187], v[200:203], v[24:27]
	v_mfma_f32_16x16x32_bf16 v[16:19], v[168:171], v[208:211], v[16:19]
	v_mfma_f32_16x16x32_bf16 v[8:11], v[184:187], v[208:211], v[8:11]
	v_mfma_f32_16x16x32_bf16 v[4:7], v[168:171], v[216:219], v[4:7]
	v_mfma_f32_16x16x32_bf16 v[0:3], v[184:187], v[216:219], v[0:3]
	s_barrier
	s_add_i32 s72, 0, 0x18000
	s_add_i32 s75, 0, 0x1c000
	v_add_u32_e32 v160, s72, v148
	v_add_u32_e32 v178, s75, v148
	ds_read_b128 v[144:147], v160
	ds_read_b128 v[152:155], v160 offset:1024
	ds_read_b128 v[156:159], v160 offset:2048
	ds_read_b128 v[160:163], v160 offset:3072
	ds_read_b128 v[164:167], v178
	ds_read_b128 v[168:171], v178 offset:1024
	ds_read_b128 v[172:175], v178 offset:2048
	ds_read_b128 v[184:187], v178 offset:3072
	s_add_u32 s50, s66, 0x40000
	s_addc_u32 s51, s67, 0
	s_mov_b32 m0, s73
	v_lshl_add_u64 v[246:247], s[50:51], 0, v[138:139]
	ds_read_b128 v[188:191], v150 offset:32768
	ds_read_b128 v[192:195], v150 offset:33792
	ds_read_b128 v[196:199], v150 offset:34816
	ds_read_b128 v[200:203], v150 offset:35840
	ds_read_b128 v[204:207], v150 offset:36864
	ds_read_b128 v[208:211], v150 offset:37888
	ds_read_b128 v[212:215], v150 offset:38912
	ds_read_b128 v[216:219], v150 offset:39936
	global_load_lds_dwordx4 v[246:247], off
	v_lshl_add_u64 v[246:247], s[50:51], 0, v[134:135]
	s_mov_b32 m0, s74
	s_nop 0
	global_load_lds_dwordx4 v[246:247], off
	s_waitcnt vmcnt(8)
	s_waitcnt lgkmcnt(0)
	s_barrier
	s_waitcnt lgkmcnt(0)
	v_mfma_f32_16x16x32_bf16 v[130:133], v[144:147], v[188:191], v[130:133]
	v_mfma_f32_16x16x32_bf16 v[126:129], v[156:159], v[188:191], v[126:129]
	v_mfma_f32_16x16x32_bf16 v[122:125], v[144:147], v[196:199], v[122:125]
	v_mfma_f32_16x16x32_bf16 v[114:117], v[156:159], v[196:199], v[114:117]
	v_mfma_f32_16x16x32_bf16 v[106:109], v[144:147], v[204:207], v[106:109]
	v_mfma_f32_16x16x32_bf16 v[98:101], v[156:159], v[204:207], v[98:101]
	v_mfma_f32_16x16x32_bf16 v[86:89], v[144:147], v[212:215], v[86:89]
	v_mfma_f32_16x16x32_bf16 v[78:81], v[156:159], v[212:215], v[78:81]
	v_mfma_f32_16x16x32_bf16 v[130:133], v[152:155], v[192:195], v[130:133]
	v_mfma_f32_16x16x32_bf16 v[126:129], v[160:163], v[192:195], v[126:129]
	v_mfma_f32_16x16x32_bf16 v[122:125], v[152:155], v[200:203], v[122:125]
	v_mfma_f32_16x16x32_bf16 v[114:117], v[160:163], v[200:203], v[114:117]
	v_mfma_f32_16x16x32_bf16 v[106:109], v[152:155], v[208:211], v[106:109]
	v_mfma_f32_16x16x32_bf16 v[98:101], v[160:163], v[208:211], v[98:101]
	v_mfma_f32_16x16x32_bf16 v[86:89], v[152:155], v[216:219], v[86:89]
	v_mfma_f32_16x16x32_bf16 v[78:81], v[160:163], v[216:219], v[78:81]
	v_mfma_f32_16x16x32_bf16 v[118:121], v[164:167], v[188:191], v[118:121]
	v_mfma_f32_16x16x32_bf16 v[110:113], v[172:175], v[188:191], v[110:113]
	v_mfma_f32_16x16x32_bf16 v[102:105], v[164:167], v[196:199], v[102:105]
	v_mfma_f32_16x16x32_bf16 v[94:97], v[172:175], v[196:199], v[94:97]
	v_mfma_f32_16x16x32_bf16 v[90:93], v[164:167], v[204:207], v[90:93]
	v_mfma_f32_16x16x32_bf16 v[82:85], v[172:175], v[204:207], v[82:85]
	v_mfma_f32_16x16x32_bf16 v[74:77], v[164:167], v[212:215], v[74:77]
	v_mfma_f32_16x16x32_bf16 v[70:73], v[172:175], v[212:215], v[70:73]
	v_mfma_f32_16x16x32_bf16 v[118:121], v[168:171], v[192:195], v[118:121]
	v_mfma_f32_16x16x32_bf16 v[110:113], v[184:187], v[192:195], v[110:113]
	v_mfma_f32_16x16x32_bf16 v[102:105], v[168:171], v[200:203], v[102:105]
	v_mfma_f32_16x16x32_bf16 v[94:97], v[184:187], v[200:203], v[94:97]
	v_mfma_f32_16x16x32_bf16 v[90:93], v[168:171], v[208:211], v[90:93]
	v_mfma_f32_16x16x32_bf16 v[82:85], v[184:187], v[208:211], v[82:85]
	v_mfma_f32_16x16x32_bf16 v[74:77], v[168:171], v[216:219], v[74:77]
	v_mfma_f32_16x16x32_bf16 v[70:73], v[184:187], v[216:219], v[70:73]
	s_barrier
	s_add_i32 s50, s72, s70
	v_lshl_add_u64 v[176:177], v[176:177], 0, s[88:89]
	s_mov_b32 m0, s50
	ds_read_b128 v[188:191], v150 offset:49152
	ds_read_b128 v[192:195], v150 offset:50176
	ds_read_b128 v[196:199], v150 offset:51200
	ds_read_b128 v[200:203], v150 offset:52224
	ds_read_b128 v[204:207], v150 offset:53248
	ds_read_b128 v[208:211], v150 offset:54272
	ds_read_b128 v[212:215], v150 offset:55296
	ds_read_b128 v[216:219], v150 offset:56320
	global_load_lds_dwordx4 v[176:177], off
	s_add_i32 m0, s50, 0x2000
	s_add_u32 s34, s34, 0x40080
	v_lshl_add_u64 v[176:177], v[220:221], 0, s[88:89]
	s_addc_u32 s35, s35, 0
	s_add_i32 s50, s75, s70
	global_load_lds_dwordx4 v[176:177], off
	v_lshl_add_u64 v[176:177], s[34:35], 0, v[136:137]
	s_mov_b32 m0, s50
	s_nop 0
	global_load_lds_dwordx4 v[176:177], off
	v_lshl_add_u64 v[176:177], s[34:35], 0, v[34:35]
	s_add_i32 m0, s50, 0x2000
	s_nop 0
	global_load_lds_dwordx4 v[176:177], off
	v_lshl_add_u64 v[176:177], v[222:223], 0, s[88:89]
	s_mov_b32 m0, s76
	s_nop 0
	global_load_lds_dwordx4 v[176:177], off
	v_lshl_add_u64 v[176:177], v[224:225], 0, s[88:89]
	s_mov_b32 m0, s77
	s_nop 0
	global_load_lds_dwordx4 v[176:177], off
	s_waitcnt vmcnt(8)
	s_waitcnt lgkmcnt(0)
	s_barrier
	s_waitcnt lgkmcnt(0)
	v_mfma_f32_16x16x32_bf16 v[66:69], v[144:147], v[188:191], v[66:69]
	v_mfma_f32_16x16x32_bf16 v[62:65], v[156:159], v[188:191], v[62:65]
	v_mfma_f32_16x16x32_bf16 v[58:61], v[144:147], v[196:199], v[58:61]
	v_mfma_f32_16x16x32_bf16 v[50:53], v[156:159], v[196:199], v[50:53]
	v_mfma_f32_16x16x32_bf16 v[42:45], v[144:147], v[204:207], v[42:45]
	v_mfma_f32_16x16x32_bf16 v[28:31], v[156:159], v[204:207], v[28:31]
	v_mfma_f32_16x16x32_bf16 v[20:23], v[144:147], v[212:215], v[20:23]
	v_mfma_f32_16x16x32_bf16 v[12:15], v[156:159], v[212:215], v[12:15]
	v_mfma_f32_16x16x32_bf16 v[66:69], v[152:155], v[192:195], v[66:69]
	v_mfma_f32_16x16x32_bf16 v[62:65], v[160:163], v[192:195], v[62:65]
	v_mfma_f32_16x16x32_bf16 v[58:61], v[152:155], v[200:203], v[58:61]
	v_mfma_f32_16x16x32_bf16 v[50:53], v[160:163], v[200:203], v[50:53]
	v_mfma_f32_16x16x32_bf16 v[42:45], v[152:155], v[208:211], v[42:45]
	v_mfma_f32_16x16x32_bf16 v[28:31], v[160:163], v[208:211], v[28:31]
	v_mfma_f32_16x16x32_bf16 v[20:23], v[152:155], v[216:219], v[20:23]
	v_mfma_f32_16x16x32_bf16 v[12:15], v[160:163], v[216:219], v[12:15]
	v_mfma_f32_16x16x32_bf16 v[54:57], v[164:167], v[188:191], v[54:57]
	v_mfma_f32_16x16x32_bf16 v[46:49], v[172:175], v[188:191], v[46:49]
	v_mfma_f32_16x16x32_bf16 v[38:41], v[164:167], v[196:199], v[38:41]
	v_mfma_f32_16x16x32_bf16 v[24:27], v[172:175], v[196:199], v[24:27]
	v_mfma_f32_16x16x32_bf16 v[16:19], v[164:167], v[204:207], v[16:19]
	v_mfma_f32_16x16x32_bf16 v[8:11], v[172:175], v[204:207], v[8:11]
	v_mfma_f32_16x16x32_bf16 v[4:7], v[164:167], v[212:215], v[4:7]
	v_mfma_f32_16x16x32_bf16 v[0:3], v[172:175], v[212:215], v[0:3]
	v_mfma_f32_16x16x32_bf16 v[54:57], v[168:171], v[192:195], v[54:57]
	v_mfma_f32_16x16x32_bf16 v[46:49], v[184:187], v[192:195], v[46:49]
	v_mfma_f32_16x16x32_bf16 v[38:41], v[168:171], v[200:203], v[38:41]
	v_mfma_f32_16x16x32_bf16 v[24:27], v[184:187], v[200:203], v[24:27]
	v_mfma_f32_16x16x32_bf16 v[16:19], v[168:171], v[208:211], v[16:19]
	v_mfma_f32_16x16x32_bf16 v[8:11], v[184:187], v[208:211], v[8:11]
	v_mfma_f32_16x16x32_bf16 v[4:7], v[168:171], v[216:219], v[4:7]
	v_mfma_f32_16x16x32_bf16 v[0:3], v[184:187], v[216:219], v[0:3]
	s_barrier
	s_add_i32 vcc_hi, vcc_hi, 2
	s_add_u32 s26, s26, 0x100
	s_addc_u32 s27, s27, 0
	s_add_u32 s57, s57, 0x100
	s_addc_u32 vcc_lo, vcc_lo, 0
	s_cmp_gt_u32 vcc_hi, 13
	s_cbranch_scc0 .LBB0_184
	s_setprio 0
	s_and_b64 vcc, exec, s[52:53]
	s_cbranch_vccnz .LBB0_189
	s_cmp_gt_i32 s62, 3
	s_mov_b64 s[26:27], -1
	s_cbranch_scc1 .LBB0_190
